# v45 + GLA stage-1 projection: batch the 4 ds_read_b128 of each 16-wide dot up front into 4 register quads with counted lgkmcnt waits (15 groups)
# baseline (speedup 1.0000x reference)
; DEVI void gla_seq(const Params& p, int l, int item, char* lds) {
;     ...
;     float bcum[16];
;     {
;       float run = 0.f;
; #pragma unroll
;       for (int ii = 0; ii < 16; ++ii) {
;         const float* gr_ = gas + (seg * 16 + ii) * 16;
;         float z = ba;
; #pragma unroll
;         for (int r = 0; r < 16; ++r) z += gr_[r] * w2[r];
;         const float ls = fminf(z, 0.f) - __logf(1.f + __expf(-fabsf(z)));
;         run += ls * (1.f / 16.f);
;         bcum[ii] = run;
;       }
;       segtot[seg * 128 + d] = run;
;     }
;     __syncthreads();
.LBB0_399:
	ds_read_b128 v[16:19], v127
	ds_read_b128 v[20:23], v127 offset:16
	ds_read_b128 v[24:27], v127 offset:32
	ds_read_b128 v[28:31], v127 offset:48
	s_mov_b32 s29, 0x3f317217
	s_waitcnt lgkmcnt(3)
	v_fma_f32 v16, v106, v16, v122
	v_fmac_f32_e32 v16, v107, v17
	v_fmac_f32_e32 v16, v108, v18
	v_fmac_f32_e32 v16, v109, v19
	s_waitcnt lgkmcnt(2)
	v_fmac_f32_e32 v16, v110, v20
	v_fmac_f32_e32 v16, v111, v21
	v_fmac_f32_e32 v16, v112, v22
	v_fmac_f32_e32 v16, v113, v23
	s_waitcnt lgkmcnt(1)
	v_fmac_f32_e32 v16, v114, v24
	v_fmac_f32_e32 v16, v115, v25
	v_fmac_f32_e32 v16, v116, v26
	v_fmac_f32_e32 v16, v117, v27
	s_waitcnt lgkmcnt(0)
	v_fmac_f32_e32 v16, v118, v28
	v_fmac_f32_e32 v16, v119, v29
	v_fmac_f32_e32 v16, v120, v30
	v_fmac_f32_e32 v16, v121, v31
	v_min_f32_e32 v17, 0, v16
	v_mul_f32_e64 v16, |v16|, s54
	v_exp_f32_e32 v16, v16
	s_mov_b32 s27, 0x7f800000
	v_add_f32_e32 v16, 1.0, v16
	s_nop 1
	v_log_f32_e32 v16, v16
	s_nop 0
	v_mul_f32_e32 v18, 0x3f317217, v16
	v_fma_f32 v18, v16, s29, -v18
	v_fmac_f32_e32 v18, 0x3377d1cf, v16
	v_fmac_f32_e32 v18, 0x3f317217, v16
	s_nop 1
	v_sub_f32_e32 v16, v17, v18
	s_mov_b32 s2, 0x3d800000
	v_fma_f32 v20, v16, s2, 0
	ds_read_b128 v[16:19], v127 offset:64
	ds_read_b128 v[230:233], v127 offset:80
	ds_read_b128 v[234:237], v127 offset:96
	ds_read_b128 v[238:241], v127 offset:112
	s_waitcnt lgkmcnt(3)
	v_fma_f32 v21, v106, v16, v122
	v_fmac_f32_e32 v21, v107, v17
	v_fmac_f32_e32 v21, v108, v18
	v_fmac_f32_e32 v21, v109, v19
	s_waitcnt lgkmcnt(2)
	v_fmac_f32_e32 v21, v110, v230
	v_fmac_f32_e32 v21, v111, v231
	v_fmac_f32_e32 v21, v112, v232
	v_fmac_f32_e32 v21, v113, v233
	s_waitcnt lgkmcnt(1)
	v_fmac_f32_e32 v21, v114, v234
	v_fmac_f32_e32 v21, v115, v235
	v_fmac_f32_e32 v21, v116, v236
	v_fmac_f32_e32 v21, v117, v237
	s_waitcnt lgkmcnt(0)
	v_fmac_f32_e32 v21, v118, v238
	v_fmac_f32_e32 v21, v119, v239
	v_fmac_f32_e32 v21, v120, v240
	v_fmac_f32_e32 v21, v121, v241
	v_mul_f32_e64 v17, |v21|, s54
	v_exp_f32_e32 v17, v17
	v_min_f32_e32 v16, 0, v21
	v_add_f32_e32 v17, 1.0, v17
	s_nop 1
	v_log_f32_e32 v17, v17
	s_nop 0
	v_mul_f32_e32 v18, 0x3f317217, v17
	v_fma_f32 v18, v17, s29, -v18
	v_fmac_f32_e32 v18, 0x3377d1cf, v17
	v_fmac_f32_e32 v18, 0x3f317217, v17
	s_nop 1
	v_sub_f32_e32 v16, v16, v18
	v_fmamk_f32 v21, v16, 0x3d800000, v20
	ds_read_b128 v[16:19], v127 offset:128
	ds_read_b128 v[230:233], v127 offset:144
	ds_read_b128 v[234:237], v127 offset:160
	ds_read_b128 v[238:241], v127 offset:176
	s_waitcnt lgkmcnt(3)
	v_fma_f32 v22, v106, v16, v122
	v_fmac_f32_e32 v22, v107, v17
	v_fmac_f32_e32 v22, v108, v18
	v_fmac_f32_e32 v22, v109, v19
	s_waitcnt lgkmcnt(2)
	v_fmac_f32_e32 v22, v110, v230
	v_fmac_f32_e32 v22, v111, v231
	v_fmac_f32_e32 v22, v112, v232
	v_fmac_f32_e32 v22, v113, v233
	s_waitcnt lgkmcnt(1)
	v_fmac_f32_e32 v22, v114, v234
	v_fmac_f32_e32 v22, v115, v235
	v_fmac_f32_e32 v22, v116, v236
	v_fmac_f32_e32 v22, v117, v237
	s_waitcnt lgkmcnt(0)
	v_fmac_f32_e32 v22, v118, v238
	v_fmac_f32_e32 v22, v119, v239
	v_fmac_f32_e32 v22, v120, v240
	v_fmac_f32_e32 v22, v121, v241
	v_mul_f32_e64 v17, |v22|, s54
	v_exp_f32_e32 v17, v17
	v_min_f32_e32 v16, 0, v22
	v_add_f32_e32 v17, 1.0, v17
	s_nop 1
	v_log_f32_e32 v17, v17
	s_nop 0
	v_mul_f32_e32 v18, 0x3f317217, v17
	v_fma_f32 v18, v17, s29, -v18
	v_fmac_f32_e32 v18, 0x3377d1cf, v17
	v_fmac_f32_e32 v18, 0x3f317217, v17
	s_nop 1
	v_sub_f32_e32 v16, v16, v18
	v_fmamk_f32 v22, v16, 0x3d800000, v21
	ds_read_b128 v[16:19], v127 offset:192
	ds_read_b128 v[230:233], v127 offset:208
	ds_read_b128 v[234:237], v127 offset:224
	ds_read_b128 v[238:241], v127 offset:240
	s_waitcnt lgkmcnt(3)
	v_fma_f32 v23, v106, v16, v122
	v_fmac_f32_e32 v23, v107, v17
	v_fmac_f32_e32 v23, v108, v18
	v_fmac_f32_e32 v23, v109, v19
	s_waitcnt lgkmcnt(2)
	v_fmac_f32_e32 v23, v110, v230
	v_fmac_f32_e32 v23, v111, v231
	v_fmac_f32_e32 v23, v112, v232
	v_fmac_f32_e32 v23, v113, v233
	s_waitcnt lgkmcnt(1)
	v_fmac_f32_e32 v23, v114, v234
	v_fmac_f32_e32 v23, v115, v235
	v_fmac_f32_e32 v23, v116, v236
	v_fmac_f32_e32 v23, v117, v237
	s_waitcnt lgkmcnt(0)
	v_fmac_f32_e32 v23, v118, v238
	v_fmac_f32_e32 v23, v119, v239
	v_fmac_f32_e32 v23, v120, v240
	v_fmac_f32_e32 v23, v121, v241
	v_mul_f32_e64 v17, |v23|, s54
	v_exp_f32_e32 v17, v17
	v_min_f32_e32 v16, 0, v23
	v_add_f32_e32 v17, 1.0, v17
	s_nop 1
	v_log_f32_e32 v17, v17
	s_nop 0
	v_mul_f32_e32 v18, 0x3f317217, v17
	v_fma_f32 v18, v17, s29, -v18
	v_fmac_f32_e32 v18, 0x3377d1cf, v17
	v_fmac_f32_e32 v18, 0x3f317217, v17
	s_nop 1
	v_sub_f32_e32 v16, v16, v18
	v_fmamk_f32 v23, v16, 0x3d800000, v22
	ds_read_b128 v[16:19], v127 offset:256
	ds_read_b128 v[230:233], v127 offset:272
	ds_read_b128 v[234:237], v127 offset:288
	ds_read_b128 v[238:241], v127 offset:304
	s_waitcnt lgkmcnt(3)
	v_fma_f32 v24, v106, v16, v122
	v_fmac_f32_e32 v24, v107, v17
	v_fmac_f32_e32 v24, v108, v18
	v_fmac_f32_e32 v24, v109, v19
	s_waitcnt lgkmcnt(2)
	v_fmac_f32_e32 v24, v110, v230
	v_fmac_f32_e32 v24, v111, v231
	v_fmac_f32_e32 v24, v112, v232
	v_fmac_f32_e32 v24, v113, v233
	s_waitcnt lgkmcnt(1)
	v_fmac_f32_e32 v24, v114, v234
	v_fmac_f32_e32 v24, v115, v235
	v_fmac_f32_e32 v24, v116, v236
	v_fmac_f32_e32 v24, v117, v237
	s_waitcnt lgkmcnt(0)
	v_fmac_f32_e32 v24, v118, v238
	v_fmac_f32_e32 v24, v119, v239
	v_fmac_f32_e32 v24, v120, v240
	v_fmac_f32_e32 v24, v121, v241
	v_mul_f32_e64 v17, |v24|, s54
	v_exp_f32_e32 v17, v17
	v_min_f32_e32 v16, 0, v24
	v_add_f32_e32 v17, 1.0, v17
	s_nop 1
	v_log_f32_e32 v17, v17
	s_nop 0
	v_mul_f32_e32 v18, 0x3f317217, v17
	v_fma_f32 v18, v17, s29, -v18
	v_fmac_f32_e32 v18, 0x3377d1cf, v17
	v_fmac_f32_e32 v18, 0x3f317217, v17
	s_nop 1
	v_sub_f32_e32 v16, v16, v18
	v_fmamk_f32 v24, v16, 0x3d800000, v23
	ds_read_b128 v[16:19], v127 offset:320
	ds_read_b128 v[230:233], v127 offset:336
	ds_read_b128 v[234:237], v127 offset:352
	ds_read_b128 v[238:241], v127 offset:368
	s_waitcnt lgkmcnt(3)
; DEVI void gla_seq(const Params& p, int l, int item, char* lds) {
;     ...
;     float bcum[16];
;     {
;       float run = 0.f;
; #pragma unroll
;       for (int ii = 0; ii < 16; ++ii) {
;         const float* gr_ = gas + (seg * 16 + ii) * 16;
;         float z = ba;
; #pragma unroll
;         for (int r = 0; r < 16; ++r) z += gr_[r] * w2[r];
;         const float ls = fminf(z, 0.f) - __logf(1.f + __expf(-fabsf(z)));
;         run += ls * (1.f / 16.f);
;         bcum[ii] = run;
;       }
;       segtot[seg * 128 + d] = run;
;     }
;     __syncthreads();
	v_fma_f32 v25, v106, v16, v122
	v_fmac_f32_e32 v25, v107, v17
	v_fmac_f32_e32 v25, v108, v18
	v_fmac_f32_e32 v25, v109, v19
	s_waitcnt lgkmcnt(2)
	v_fmac_f32_e32 v25, v110, v230
	v_fmac_f32_e32 v25, v111, v231
	v_fmac_f32_e32 v25, v112, v232
	v_fmac_f32_e32 v25, v113, v233
	s_waitcnt lgkmcnt(1)
	v_fmac_f32_e32 v25, v114, v234
	v_fmac_f32_e32 v25, v115, v235
	v_fmac_f32_e32 v25, v116, v236
	v_fmac_f32_e32 v25, v117, v237
	s_waitcnt lgkmcnt(0)
	v_fmac_f32_e32 v25, v118, v238
	v_fmac_f32_e32 v25, v119, v239
	v_fmac_f32_e32 v25, v120, v240
	v_fmac_f32_e32 v25, v121, v241
	v_mul_f32_e64 v17, |v25|, s54
	v_exp_f32_e32 v17, v17
	v_min_f32_e32 v16, 0, v25
	v_add_f32_e32 v17, 1.0, v17
	s_nop 1
	v_log_f32_e32 v17, v17
	s_nop 0
	v_mul_f32_e32 v18, 0x3f317217, v17
	v_fma_f32 v18, v17, s29, -v18
	v_fmac_f32_e32 v18, 0x3377d1cf, v17
	v_fmac_f32_e32 v18, 0x3f317217, v17
	s_nop 1
	v_sub_f32_e32 v16, v16, v18
	v_fmamk_f32 v25, v16, 0x3d800000, v24
	ds_read_b128 v[16:19], v127 offset:384
	ds_read_b128 v[230:233], v127 offset:400
	ds_read_b128 v[234:237], v127 offset:416
	ds_read_b128 v[238:241], v127 offset:432
	s_waitcnt lgkmcnt(3)
	v_fma_f32 v26, v106, v16, v122
	v_fmac_f32_e32 v26, v107, v17
	v_fmac_f32_e32 v26, v108, v18
	v_fmac_f32_e32 v26, v109, v19
	s_waitcnt lgkmcnt(2)
	v_fmac_f32_e32 v26, v110, v230
	v_fmac_f32_e32 v26, v111, v231
	v_fmac_f32_e32 v26, v112, v232
	v_fmac_f32_e32 v26, v113, v233
	s_waitcnt lgkmcnt(1)
	v_fmac_f32_e32 v26, v114, v234
	v_fmac_f32_e32 v26, v115, v235
	v_fmac_f32_e32 v26, v116, v236
	v_fmac_f32_e32 v26, v117, v237
	s_waitcnt lgkmcnt(0)
	v_fmac_f32_e32 v26, v118, v238
	v_fmac_f32_e32 v26, v119, v239
	v_fmac_f32_e32 v26, v120, v240
	v_fmac_f32_e32 v26, v121, v241
	v_mul_f32_e64 v17, |v26|, s54
	v_exp_f32_e32 v17, v17
	v_min_f32_e32 v16, 0, v26
	v_add_f32_e32 v17, 1.0, v17
	s_nop 1
	v_log_f32_e32 v17, v17
	s_nop 0
	v_mul_f32_e32 v18, 0x3f317217, v17
	v_fma_f32 v18, v17, s29, -v18
	v_fmac_f32_e32 v18, 0x3377d1cf, v17
	v_fmac_f32_e32 v18, 0x3f317217, v17
	s_nop 1
	v_sub_f32_e32 v16, v16, v18
	v_fmamk_f32 v26, v16, 0x3d800000, v25
	ds_read_b128 v[16:19], v127 offset:448
	ds_read_b128 v[230:233], v127 offset:464
	ds_read_b128 v[234:237], v127 offset:480
	ds_read_b128 v[238:241], v127 offset:496
	s_waitcnt lgkmcnt(3)
	v_fma_f32 v27, v106, v16, v122
	v_fmac_f32_e32 v27, v107, v17
	v_fmac_f32_e32 v27, v108, v18
	v_fmac_f32_e32 v27, v109, v19
	s_waitcnt lgkmcnt(2)
	v_fmac_f32_e32 v27, v110, v230
	v_fmac_f32_e32 v27, v111, v231
	v_fmac_f32_e32 v27, v112, v232
	v_fmac_f32_e32 v27, v113, v233
	s_waitcnt lgkmcnt(1)
	v_fmac_f32_e32 v27, v114, v234
	v_fmac_f32_e32 v27, v115, v235
	v_fmac_f32_e32 v27, v116, v236
	v_fmac_f32_e32 v27, v117, v237
	s_waitcnt lgkmcnt(0)
	v_fmac_f32_e32 v27, v118, v238
	v_fmac_f32_e32 v27, v119, v239
	v_fmac_f32_e32 v27, v120, v240
	v_fmac_f32_e32 v27, v121, v241
	v_mul_f32_e64 v17, |v27|, s54
	v_exp_f32_e32 v17, v17
	v_min_f32_e32 v16, 0, v27
	v_add_f32_e32 v17, 1.0, v17
	s_nop 1
	v_log_f32_e32 v17, v17
	s_nop 0
	v_mul_f32_e32 v18, 0x3f317217, v17
	v_fma_f32 v18, v17, s29, -v18
	v_fmac_f32_e32 v18, 0x3377d1cf, v17
	v_fmac_f32_e32 v18, 0x3f317217, v17
	s_nop 1
	v_sub_f32_e32 v16, v16, v18
	v_fmamk_f32 v27, v16, 0x3d800000, v26
	ds_read_b128 v[16:19], v127 offset:512
	ds_read_b128 v[230:233], v127 offset:528
	ds_read_b128 v[234:237], v127 offset:544
	ds_read_b128 v[238:241], v127 offset:560
	s_waitcnt lgkmcnt(3)
	v_fma_f32 v28, v106, v16, v122
	v_fmac_f32_e32 v28, v107, v17
	v_fmac_f32_e32 v28, v108, v18
	v_fmac_f32_e32 v28, v109, v19
	s_waitcnt lgkmcnt(2)
	v_fmac_f32_e32 v28, v110, v230
	v_fmac_f32_e32 v28, v111, v231
	v_fmac_f32_e32 v28, v112, v232
	v_fmac_f32_e32 v28, v113, v233
	s_waitcnt lgkmcnt(1)
	v_fmac_f32_e32 v28, v114, v234
	v_fmac_f32_e32 v28, v115, v235
	v_fmac_f32_e32 v28, v116, v236
	v_fmac_f32_e32 v28, v117, v237
	s_waitcnt lgkmcnt(0)
	v_fmac_f32_e32 v28, v118, v238
	v_fmac_f32_e32 v28, v119, v239
	v_fmac_f32_e32 v28, v120, v240
	v_fmac_f32_e32 v28, v121, v241
	v_mul_f32_e64 v17, |v28|, s54
	v_exp_f32_e32 v17, v17
	v_min_f32_e32 v16, 0, v28
	v_add_f32_e32 v17, 1.0, v17
	s_nop 1
	v_log_f32_e32 v17, v17
	s_nop 0
	v_mul_f32_e32 v18, 0x3f317217, v17
	v_fma_f32 v18, v17, s29, -v18
	v_fmac_f32_e32 v18, 0x3377d1cf, v17
	v_fmac_f32_e32 v18, 0x3f317217, v17
	s_nop 1
	v_sub_f32_e32 v16, v16, v18
	v_fmamk_f32 v28, v16, 0x3d800000, v27
	ds_read_b128 v[16:19], v127 offset:576
	ds_read_b128 v[230:233], v127 offset:592
	ds_read_b128 v[234:237], v127 offset:608
	ds_read_b128 v[238:241], v127 offset:624
	s_waitcnt lgkmcnt(3)
	v_fma_f32 v29, v106, v16, v122
	v_fmac_f32_e32 v29, v107, v17
	v_fmac_f32_e32 v29, v108, v18
	v_fmac_f32_e32 v29, v109, v19
	s_waitcnt lgkmcnt(2)
	v_fmac_f32_e32 v29, v110, v230
	v_fmac_f32_e32 v29, v111, v231
	v_fmac_f32_e32 v29, v112, v232
	v_fmac_f32_e32 v29, v113, v233
	s_waitcnt lgkmcnt(1)
	v_fmac_f32_e32 v29, v114, v234
	v_fmac_f32_e32 v29, v115, v235
	v_fmac_f32_e32 v29, v116, v236
	v_fmac_f32_e32 v29, v117, v237
	s_waitcnt lgkmcnt(0)
	v_fmac_f32_e32 v29, v118, v238
	v_fmac_f32_e32 v29, v119, v239
	v_fmac_f32_e32 v29, v120, v240
	v_fmac_f32_e32 v29, v121, v241
	v_mul_f32_e64 v17, |v29|, s54
	v_exp_f32_e32 v17, v17
	v_min_f32_e32 v16, 0, v29
	v_add_f32_e32 v17, 1.0, v17
	s_nop 1
	v_log_f32_e32 v17, v17
	s_nop 0
	v_mul_f32_e32 v18, 0x3f317217, v17
	v_fma_f32 v18, v17, s29, -v18
	v_fmac_f32_e32 v18, 0x3377d1cf, v17
	v_fmac_f32_e32 v18, 0x3f317217, v17
	s_nop 1
	v_sub_f32_e32 v16, v16, v18
	v_fmamk_f32 v29, v16, 0x3d800000, v28
	ds_read_b128 v[16:19], v127 offset:640
	ds_read_b128 v[230:233], v127 offset:656
	ds_read_b128 v[234:237], v127 offset:672
	ds_read_b128 v[238:241], v127 offset:688
	s_waitcnt lgkmcnt(3)
; DEVI void gla_seq(const Params& p, int l, int item, char* lds) {
;     ...
;     float bcum[16];
;     {
;       float run = 0.f;
; #pragma unroll
;       for (int ii = 0; ii < 16; ++ii) {
;         const float* gr_ = gas + (seg * 16 + ii) * 16;
;         float z = ba;
; #pragma unroll
;         for (int r = 0; r < 16; ++r) z += gr_[r] * w2[r];
;         const float ls = fminf(z, 0.f) - __logf(1.f + __expf(-fabsf(z)));
;         run += ls * (1.f / 16.f);
;         bcum[ii] = run;
;       }
;       segtot[seg * 128 + d] = run;
;     }
;     __syncthreads();
	v_fma_f32 v30, v106, v16, v122
	v_fmac_f32_e32 v30, v107, v17
	v_fmac_f32_e32 v30, v108, v18
	v_fmac_f32_e32 v30, v109, v19
	s_waitcnt lgkmcnt(2)
	v_fmac_f32_e32 v30, v110, v230
	v_fmac_f32_e32 v30, v111, v231
	v_fmac_f32_e32 v30, v112, v232
	v_fmac_f32_e32 v30, v113, v233
	s_waitcnt lgkmcnt(1)
	v_fmac_f32_e32 v30, v114, v234
	v_fmac_f32_e32 v30, v115, v235
	v_fmac_f32_e32 v30, v116, v236
	v_fmac_f32_e32 v30, v117, v237
	s_waitcnt lgkmcnt(0)
	v_fmac_f32_e32 v30, v118, v238
	v_fmac_f32_e32 v30, v119, v239
	v_fmac_f32_e32 v30, v120, v240
	v_fmac_f32_e32 v30, v121, v241
	v_mul_f32_e64 v17, |v30|, s54
	v_exp_f32_e32 v17, v17
	v_min_f32_e32 v16, 0, v30
	v_add_f32_e32 v17, 1.0, v17
	s_nop 1
	v_log_f32_e32 v17, v17
	s_nop 0
	v_mul_f32_e32 v18, 0x3f317217, v17
	v_fma_f32 v18, v17, s29, -v18
	v_fmac_f32_e32 v18, 0x3377d1cf, v17
	v_fmac_f32_e32 v18, 0x3f317217, v17
	s_nop 1
	v_sub_f32_e32 v16, v16, v18
	v_fmamk_f32 v30, v16, 0x3d800000, v29
	ds_read_b128 v[16:19], v127 offset:704
	ds_read_b128 v[230:233], v127 offset:720
	ds_read_b128 v[234:237], v127 offset:736
	ds_read_b128 v[238:241], v127 offset:752
	s_waitcnt lgkmcnt(3)
	v_fma_f32 v31, v106, v16, v122
	v_fmac_f32_e32 v31, v107, v17
	v_fmac_f32_e32 v31, v108, v18
	v_fmac_f32_e32 v31, v109, v19
	s_waitcnt lgkmcnt(2)
	v_fmac_f32_e32 v31, v110, v230
	v_fmac_f32_e32 v31, v111, v231
	v_fmac_f32_e32 v31, v112, v232
	v_fmac_f32_e32 v31, v113, v233
	s_waitcnt lgkmcnt(1)
	v_fmac_f32_e32 v31, v114, v234
	v_fmac_f32_e32 v31, v115, v235
	v_fmac_f32_e32 v31, v116, v236
	v_fmac_f32_e32 v31, v117, v237
	s_waitcnt lgkmcnt(0)
	v_fmac_f32_e32 v31, v118, v238
	v_fmac_f32_e32 v31, v119, v239
	v_fmac_f32_e32 v31, v120, v240
	v_fmac_f32_e32 v31, v121, v241
	v_mul_f32_e64 v17, |v31|, s54
	v_exp_f32_e32 v17, v17
	v_min_f32_e32 v16, 0, v31
	v_add_f32_e32 v17, 1.0, v17
	s_nop 1
	v_log_f32_e32 v17, v17
	s_nop 0
	v_mul_f32_e32 v18, 0x3f317217, v17
	v_fma_f32 v18, v17, s29, -v18
	v_fmac_f32_e32 v18, 0x3377d1cf, v17
	v_fmac_f32_e32 v18, 0x3f317217, v17
	s_nop 1
	v_sub_f32_e32 v16, v16, v18
	v_fmamk_f32 v31, v16, 0x3d800000, v30
	ds_read_b128 v[16:19], v127 offset:768
	ds_read_b128 v[230:233], v127 offset:784
	ds_read_b128 v[234:237], v127 offset:800
	ds_read_b128 v[238:241], v127 offset:816
	s_waitcnt lgkmcnt(3)
	v_fma_f32 v32, v106, v16, v122
	v_fmac_f32_e32 v32, v107, v17
	v_fmac_f32_e32 v32, v108, v18
	v_fmac_f32_e32 v32, v109, v19
	s_waitcnt lgkmcnt(2)
	v_fmac_f32_e32 v32, v110, v230
	v_fmac_f32_e32 v32, v111, v231
	v_fmac_f32_e32 v32, v112, v232
	v_fmac_f32_e32 v32, v113, v233
	s_waitcnt lgkmcnt(1)
	v_fmac_f32_e32 v32, v114, v234
	v_fmac_f32_e32 v32, v115, v235
	v_fmac_f32_e32 v32, v116, v236
	v_fmac_f32_e32 v32, v117, v237
	s_waitcnt lgkmcnt(0)
	v_fmac_f32_e32 v32, v118, v238
	v_fmac_f32_e32 v32, v119, v239
	v_fmac_f32_e32 v32, v120, v240
	v_fmac_f32_e32 v32, v121, v241
	v_mul_f32_e64 v17, |v32|, s54
	v_exp_f32_e32 v17, v17
	v_min_f32_e32 v16, 0, v32
	v_add_f32_e32 v17, 1.0, v17
	s_nop 1
	v_log_f32_e32 v17, v17
	s_nop 0
	v_mul_f32_e32 v18, 0x3f317217, v17
	v_fma_f32 v18, v17, s29, -v18
	v_fmac_f32_e32 v18, 0x3377d1cf, v17
	v_fmac_f32_e32 v18, 0x3f317217, v17
	s_nop 1
	v_sub_f32_e32 v16, v16, v18
	v_fmamk_f32 v32, v16, 0x3d800000, v31
	ds_read_b128 v[16:19], v127 offset:832
	ds_read_b128 v[230:233], v127 offset:848
	ds_read_b128 v[234:237], v127 offset:864
	ds_read_b128 v[238:241], v127 offset:880
	s_waitcnt lgkmcnt(3)
	v_fma_f32 v33, v106, v16, v122
	v_fmac_f32_e32 v33, v107, v17
	v_fmac_f32_e32 v33, v108, v18
	v_fmac_f32_e32 v33, v109, v19
	s_waitcnt lgkmcnt(2)
	v_fmac_f32_e32 v33, v110, v230
	v_fmac_f32_e32 v33, v111, v231
	v_fmac_f32_e32 v33, v112, v232
	v_fmac_f32_e32 v33, v113, v233
	s_waitcnt lgkmcnt(1)
	v_fmac_f32_e32 v33, v114, v234
	v_fmac_f32_e32 v33, v115, v235
	v_fmac_f32_e32 v33, v116, v236
	v_fmac_f32_e32 v33, v117, v237
	s_waitcnt lgkmcnt(0)
	v_fmac_f32_e32 v33, v118, v238
	v_fmac_f32_e32 v33, v119, v239
	v_fmac_f32_e32 v33, v120, v240
	v_fmac_f32_e32 v33, v121, v241
	v_mul_f32_e64 v17, |v33|, s54
	v_exp_f32_e32 v17, v17
	v_min_f32_e32 v16, 0, v33
	v_add_f32_e32 v17, 1.0, v17
	s_nop 1
	v_log_f32_e32 v17, v17
	s_nop 0
	v_mul_f32_e32 v18, 0x3f317217, v17
	v_fma_f32 v18, v17, s29, -v18
	v_fmac_f32_e32 v18, 0x3377d1cf, v17
	v_fmac_f32_e32 v18, 0x3f317217, v17
	s_nop 1
	v_sub_f32_e32 v16, v16, v18
	v_fmamk_f32 v33, v16, 0x3d800000, v32
	ds_read_b128 v[16:19], v127 offset:896
	ds_read_b128 v[230:233], v127 offset:912
	ds_read_b128 v[234:237], v127 offset:928
	ds_read_b128 v[238:241], v127 offset:944
	s_waitcnt lgkmcnt(3)
	v_fma_f32 v34, v106, v16, v122
	v_fmac_f32_e32 v34, v107, v17
	v_fmac_f32_e32 v34, v108, v18
	v_fmac_f32_e32 v34, v109, v19
	s_waitcnt lgkmcnt(2)
	v_fmac_f32_e32 v34, v110, v230
	v_fmac_f32_e32 v34, v111, v231
	v_fmac_f32_e32 v34, v112, v232
	v_fmac_f32_e32 v34, v113, v233
	s_waitcnt lgkmcnt(1)
	v_fmac_f32_e32 v34, v114, v234
	v_fmac_f32_e32 v34, v115, v235
	v_fmac_f32_e32 v34, v116, v236
	v_fmac_f32_e32 v34, v117, v237
	s_waitcnt lgkmcnt(0)
	v_fmac_f32_e32 v34, v118, v238
	v_fmac_f32_e32 v34, v119, v239
	v_fmac_f32_e32 v34, v120, v240
	v_fmac_f32_e32 v34, v121, v241
	v_mul_f32_e64 v17, |v34|, s54
	v_exp_f32_e32 v17, v17
	v_min_f32_e32 v16, 0, v34
	v_add_f32_e32 v17, 1.0, v17
	s_nop 1
	v_log_f32_e32 v17, v17
	s_nop 0
	v_mul_f32_e32 v18, 0x3f317217, v17
	v_fma_f32 v18, v17, s29, -v18
	v_fmac_f32_e32 v18, 0x3377d1cf, v17
	v_fmac_f32_e32 v18, 0x3f317217, v17
	s_nop 1
	v_sub_f32_e32 v16, v16, v18
	v_fmamk_f32 v34, v16, 0x3d800000, v33
	ds_read_b128 v[16:19], v127 offset:960
	ds_read_b128 v[230:233], v127 offset:976
	ds_read_b128 v[234:237], v127 offset:992
	ds_read_b128 v[238:241], v127 offset:1008
	s_waitcnt lgkmcnt(3)
	v_fma_f32 v35, v106, v16, v122
	v_fmac_f32_e32 v35, v107, v17
	v_fmac_f32_e32 v35, v108, v18
	v_fmac_f32_e32 v35, v109, v19
	s_waitcnt lgkmcnt(2)
	v_fmac_f32_e32 v35, v110, v230
	v_fmac_f32_e32 v35, v111, v231
	v_fmac_f32_e32 v35, v112, v232
	v_fmac_f32_e32 v35, v113, v233
	s_waitcnt lgkmcnt(1)
	v_fmac_f32_e32 v35, v114, v234
	v_fmac_f32_e32 v35, v115, v235
	v_fmac_f32_e32 v35, v116, v236
	v_fmac_f32_e32 v35, v117, v237
	s_waitcnt lgkmcnt(0)
	v_fmac_f32_e32 v35, v118, v238
	v_fmac_f32_e32 v35, v119, v239
	v_fmac_f32_e32 v35, v120, v240
	v_fmac_f32_e32 v35, v121, v241
	v_mul_f32_e64 v17, |v35|, s54
	v_exp_f32_e32 v17, v17
	v_min_f32_e32 v16, 0, v35
	v_add_f32_e32 v17, 1.0, v17
	s_nop 1
	v_log_f32_e32 v17, v17
	s_nop 0
	v_mul_f32_e32 v18, 0x3f317217, v17
	v_fma_f32 v18, v17, s29, -v18
	v_fmac_f32_e32 v18, 0x3377d1cf, v17
	v_fmac_f32_e32 v18, 0x3f317217, v17
	s_nop 1
	v_sub_f32_e32 v16, v16, v18
	v_fmamk_f32 v35, v16, 0x3d800000, v34
	ds_write_b32 v128, v35
	s_waitcnt lgkmcnt(0)
	s_barrier
; DEVI u16 f2bf(float f) { return (u16)(cvtpk(f, 0.f) & 0xffffu); }
; DEVI float bf2f(u16 h) { return __uint_as_float(((unsigned)h) << 16); }
; DEVI void gla_seq(const Params& p, int l, int item, char* lds) {
;     ...
;     {
;       float pre = 0.f, tot = 0.f;
; #pragma unroll
;       for (int s_ = 0; s_ < 4; ++s_) { const float v = segtot[s_ * 128 + d]; tot += v; if (s_ < seg) pre += v; }
;       const float etot = __expf(tot);
;       if (seg == 0) ebl[d] = etot;
; #pragma unroll
;       for (int ii = 0; ii < 16; ++ii) {
;         const int i = seg * 16 + ii;
;         const float bb = bcum[ii] + pre;
;         const int so = i * 256 + (((d >> 3) ^ (i & 7)) << 4) + (d & 7) * 2;
;         const float q = bf2f(*(const u16*)(qs + so)), k = bf2f(*(const u16*)(ks + so));
;         const float eb = __expf(bb), ieb = __frcp_rn(eb);
;         *(u16*)(qs + so) = f2bf(q * eb);
;         *(u16*)(ks + so) = f2bf(k * ieb);
;         *(u16*)(kT + d * 144 + i * 2) = f2bf(k * (etot * ieb));
;       }
	ds_read2st64_b32 v[16:17], v129 offset1:2
	ds_read2st64_b32 v[18:19], v129 offset0:4 offset1:6
	s_waitcnt lgkmcnt(1)
	v_add_f32_e32 v36, 0, v16
	v_add_f32_e32 v16, v36, v17
	s_waitcnt lgkmcnt(0)
	v_add_f32_e32 v16, v16, v18
	v_add_f32_e32 v16, v16, v19
	v_mul_f32_e32 v16, 0x3fb8aa3b, v16
	v_exp_f32_e32 v16, v16
	s_and_saveexec_b64 s[2:3], s[6:7]
	ds_write_b32 v136, v16
	s_or_b64 exec, exec, s[2:3]
	v_cndmask_b32_e64 v36, 0, v36, s[10:11]
	v_add_f32_e32 v17, v17, v36
	v_cndmask_b32_e64 v17, v36, v17, s[12:13]
	v_add_f32_e32 v18, v18, v17
	v_cndmask_b32_e64 v17, v17, v18, s[14:15]
	v_add_f32_e32 v18, v19, v17
	v_cndmask_b32_e64 v17, v17, v18, s[16:17]
	v_add_f32_e32 v18, v20, v17
	v_mul_f32_e32 v18, 0x3fb8aa3b, v18
	v_exp_f32_e64 v36, -v18
	v_exp_f32_e32 v18, v18
	ds_read_u16 v19, v154
	ds_read_u16 v20, v154 offset:16384
	v_add_u32_e32 v187, v133, v131
	s_waitcnt lgkmcnt(1)
	v_lshlrev_b32_e32 v19, 16, v19
	s_waitcnt lgkmcnt(0)
	v_lshlrev_b32_e32 v20, 16, v20
	v_mul_f32_e32 v18, v18, v19
	v_cvt_pk_bf16_f32 v18, v18, s0
	ds_write_b16 v154, v18
	v_mul_f32_e32 v18, v36, v20
	v_cvt_pk_bf16_f32 v18, v18, s0
	ds_write_b16 v154, v18 offset:16384
	v_mul_f32_e32 v18, v16, v36
	v_mul_f32_e32 v18, v18, v20
	v_cvt_pk_bf16_f32 v18, v18, s0
	v_add_u32_e32 v19, v130, v132
	ds_write_b16 v19, v18 offset:32768
	v_add_f32_e32 v18, v21, v17
	v_mul_f32_e32 v18, 0x3fb8aa3b, v18
	v_exp_f32_e64 v21, -v18
	v_exp_f32_e32 v18, v18
	ds_read_u16 v19, v155
	ds_read_u16 v20, v155 offset:16384
	s_waitcnt lgkmcnt(1)
	v_lshlrev_b32_e32 v19, 16, v19
	s_waitcnt lgkmcnt(0)
	v_lshlrev_b32_e32 v20, 16, v20
	v_mul_f32_e32 v18, v18, v19
	v_cvt_pk_bf16_f32 v18, v18, s0
	ds_write_b16 v155, v18
	v_mul_f32_e32 v18, v21, v20
	v_cvt_pk_bf16_f32 v18, v18, s0
	ds_write_b16 v155, v18 offset:16384
	v_mul_f32_e32 v18, v16, v21
	v_mul_f32_e32 v18, v18, v20
	v_cvt_pk_bf16_f32 v18, v18, s0
	ds_write_b16 v156, v18 offset:32768
	v_add_f32_e32 v18, v22, v17
	v_mul_f32_e32 v18, 0x3fb8aa3b, v18
	v_exp_f32_e64 v21, -v18
	v_exp_f32_e32 v18, v18
	ds_read_u16 v19, v157
	ds_read_u16 v20, v157 offset:16384
	s_waitcnt lgkmcnt(1)
	v_lshlrev_b32_e32 v19, 16, v19
	s_waitcnt lgkmcnt(0)
	v_lshlrev_b32_e32 v20, 16, v20
	v_mul_f32_e32 v18, v18, v19
	v_cvt_pk_bf16_f32 v18, v18, s0
	ds_write_b16 v157, v18
	v_mul_f32_e32 v18, v21, v20
	v_cvt_pk_bf16_f32 v18, v18, s0
	ds_write_b16 v157, v18 offset:16384
	v_mul_f32_e32 v18, v16, v21
	v_mul_f32_e32 v18, v18, v20
	v_cvt_pk_bf16_f32 v18, v18, s0
	ds_write_b16 v158, v18 offset:32768
	v_add_f32_e32 v18, v23, v17
	v_mul_f32_e32 v18, 0x3fb8aa3b, v18
	v_exp_f32_e64 v21, -v18
	v_exp_f32_e32 v18, v18
	ds_read_u16 v19, v159
	ds_read_u16 v20, v159 offset:16384
	s_waitcnt lgkmcnt(1)
	v_lshlrev_b32_e32 v19, 16, v19
	s_waitcnt lgkmcnt(0)
	v_lshlrev_b32_e32 v20, 16, v20
	v_mul_f32_e32 v18, v18, v19
	v_cvt_pk_bf16_f32 v18, v18, s0
	ds_write_b16 v159, v18
	v_mul_f32_e32 v18, v21, v20
	v_cvt_pk_bf16_f32 v18, v18, s0
	ds_write_b16 v159, v18 offset:16384
	v_mul_f32_e32 v18, v16, v21
	v_mul_f32_e32 v18, v18, v20
	v_cvt_pk_bf16_f32 v18, v18, s0
	ds_write_b16 v160, v18 offset:32768
	v_add_f32_e32 v18, v24, v17
	v_mul_f32_e32 v18, 0x3fb8aa3b, v18
	v_exp_f32_e64 v21, -v18
	v_exp_f32_e32 v18, v18
	ds_read_u16 v19, v161
	ds_read_u16 v20, v161 offset:16384
	s_waitcnt lgkmcnt(1)
	v_lshlrev_b32_e32 v19, 16, v19
	s_waitcnt lgkmcnt(0)
	v_lshlrev_b32_e32 v20, 16, v20
	v_mul_f32_e32 v18, v18, v19
	v_cvt_pk_bf16_f32 v18, v18, s0
	ds_write_b16 v161, v18
	v_mul_f32_e32 v18, v21, v20
	v_cvt_pk_bf16_f32 v18, v18, s0
	ds_write_b16 v161, v18 offset:16384
	v_mul_f32_e32 v18, v16, v21
	v_mul_f32_e32 v18, v18, v20
	v_cvt_pk_bf16_f32 v18, v18, s0
	ds_write_b16 v162, v18 offset:32768
	v_add_f32_e32 v18, v25, v17
	v_mul_f32_e32 v18, 0x3fb8aa3b, v18
	v_exp_f32_e64 v21, -v18
	v_exp_f32_e32 v18, v18
	ds_read_u16 v19, v163
	ds_read_u16 v20, v163 offset:16384
	s_waitcnt lgkmcnt(1)
	v_lshlrev_b32_e32 v19, 16, v19
	s_waitcnt lgkmcnt(0)
	v_lshlrev_b32_e32 v20, 16, v20
	v_mul_f32_e32 v18, v18, v19
	v_cvt_pk_bf16_f32 v18, v18, s0
	ds_write_b16 v163, v18
	v_mul_f32_e32 v18, v21, v20
	v_cvt_pk_bf16_f32 v18, v18, s0
	ds_write_b16 v163, v18 offset:16384
	v_mul_f32_e32 v18, v16, v21
	v_mul_f32_e32 v18, v18, v20
	v_cvt_pk_bf16_f32 v18, v18, s0
	ds_write_b16 v164, v18 offset:32768
	v_add_f32_e32 v18, v26, v17
	v_mul_f32_e32 v18, 0x3fb8aa3b, v18
	v_exp_f32_e64 v21, -v18
	v_exp_f32_e32 v18, v18
	ds_read_u16 v19, v165
	ds_read_u16 v20, v165 offset:16384
	s_waitcnt lgkmcnt(1)
	v_lshlrev_b32_e32 v19, 16, v19
	s_waitcnt lgkmcnt(0)
	v_lshlrev_b32_e32 v20, 16, v20
	v_mul_f32_e32 v18, v18, v19
	v_cvt_pk_bf16_f32 v18, v18, s0
	ds_write_b16 v165, v18
	v_mul_f32_e32 v18, v21, v20
	v_cvt_pk_bf16_f32 v18, v18, s0
	ds_write_b16 v165, v18 offset:16384
	v_mul_f32_e32 v18, v16, v21
	v_mul_f32_e32 v18, v18, v20
	v_cvt_pk_bf16_f32 v18, v18, s0
	ds_write_b16 v166, v18 offset:32768
	v_add_f32_e32 v18, v27, v17
	v_mul_f32_e32 v18, 0x3fb8aa3b, v18
	v_exp_f32_e64 v21, -v18
	v_exp_f32_e32 v18, v18
	ds_read_u16 v19, v167
	ds_read_u16 v20, v167 offset:16384
	s_waitcnt lgkmcnt(1)
	v_lshlrev_b32_e32 v19, 16, v19
	s_waitcnt lgkmcnt(0)
	v_lshlrev_b32_e32 v20, 16, v20
	v_mul_f32_e32 v18, v18, v19
	v_cvt_pk_bf16_f32 v18, v18, s0
	ds_write_b16 v167, v18
	v_mul_f32_e32 v18, v21, v20
	v_cvt_pk_bf16_f32 v18, v18, s0
	ds_write_b16 v167, v18 offset:16384
	v_mul_f32_e32 v18, v16, v21
	v_mul_f32_e32 v18, v18, v20
	v_cvt_pk_bf16_f32 v18, v18, s0
	ds_write_b16 v168, v18 offset:32768
	v_add_f32_e32 v18, v28, v17
	v_mul_f32_e32 v18, 0x3fb8aa3b, v18
	v_exp_f32_e64 v21, -v18
	v_exp_f32_e32 v18, v18
	ds_read_u16 v19, v169
	ds_read_u16 v20, v169 offset:16384
	s_waitcnt lgkmcnt(1)
; DEVI u16 f2bf(float f) { return (u16)(cvtpk(f, 0.f) & 0xffffu); }
; DEVI float bf2f(u16 h) { return __uint_as_float(((unsigned)h) << 16); }
; DEVI void gla_seq(const Params& p, int l, int item, char* lds) {
;     ...
;       for (int ii = 0; ii < 16; ++ii) {
;         const int i = seg * 16 + ii;
;         const float bb = bcum[ii] + pre;
;         const int so = i * 256 + (((d >> 3) ^ (i & 7)) << 4) + (d & 7) * 2;
;         const float q = bf2f(*(const u16*)(qs + so)), k = bf2f(*(const u16*)(ks + so));
;         const float eb = __expf(bb), ieb = __frcp_rn(eb);
;         *(u16*)(qs + so) = f2bf(q * eb);
;         *(u16*)(ks + so) = f2bf(k * ieb);
;         *(u16*)(kT + d * 144 + i * 2) = f2bf(k * (etot * ieb));
;       }
;     }
;     __syncthreads();
;     const char* sTc = sT + cur * 16384; char* sTn = sT + (cur ^ 1) * 16384;
;     if (wid < 4) {
	v_lshlrev_b32_e32 v19, 16, v19
	s_waitcnt lgkmcnt(0)
	v_lshlrev_b32_e32 v20, 16, v20
	v_mul_f32_e32 v18, v18, v19
	v_cvt_pk_bf16_f32 v18, v18, s0
	ds_write_b16 v169, v18
	v_mul_f32_e32 v18, v21, v20
	v_cvt_pk_bf16_f32 v18, v18, s0
	ds_write_b16 v169, v18 offset:16384
	v_mul_f32_e32 v18, v16, v21
	v_mul_f32_e32 v18, v18, v20
	v_cvt_pk_bf16_f32 v18, v18, s0
	ds_write_b16 v170, v18 offset:32768
	v_add_f32_e32 v18, v29, v17
	v_mul_f32_e32 v18, 0x3fb8aa3b, v18
	v_exp_f32_e64 v21, -v18
	v_exp_f32_e32 v18, v18
	ds_read_u16 v19, v171
	ds_read_u16 v20, v171 offset:16384
	s_waitcnt lgkmcnt(1)
	v_lshlrev_b32_e32 v19, 16, v19
	s_waitcnt lgkmcnt(0)
	v_lshlrev_b32_e32 v20, 16, v20
	v_mul_f32_e32 v18, v18, v19
	v_cvt_pk_bf16_f32 v18, v18, s0
	ds_write_b16 v171, v18
	v_mul_f32_e32 v18, v21, v20
	v_cvt_pk_bf16_f32 v18, v18, s0
	ds_write_b16 v171, v18 offset:16384
	v_mul_f32_e32 v18, v16, v21
	v_mul_f32_e32 v18, v18, v20
	v_cvt_pk_bf16_f32 v18, v18, s0
	ds_write_b16 v172, v18 offset:32768
	v_add_f32_e32 v18, v30, v17
	v_mul_f32_e32 v18, 0x3fb8aa3b, v18
	v_exp_f32_e64 v21, -v18
	v_exp_f32_e32 v18, v18
	ds_read_u16 v19, v173
	ds_read_u16 v20, v173 offset:16384
	s_waitcnt lgkmcnt(1)
	v_lshlrev_b32_e32 v19, 16, v19
	s_waitcnt lgkmcnt(0)
	v_lshlrev_b32_e32 v20, 16, v20
	v_mul_f32_e32 v18, v18, v19
	v_cvt_pk_bf16_f32 v18, v18, s0
	ds_write_b16 v173, v18
	v_mul_f32_e32 v18, v21, v20
	v_cvt_pk_bf16_f32 v18, v18, s0
	ds_write_b16 v173, v18 offset:16384
	v_mul_f32_e32 v18, v16, v21
	v_mul_f32_e32 v18, v18, v20
	v_cvt_pk_bf16_f32 v18, v18, s0
	ds_write_b16 v174, v18 offset:32768
	v_add_f32_e32 v18, v31, v17
	v_mul_f32_e32 v18, 0x3fb8aa3b, v18
	v_exp_f32_e64 v21, -v18
	v_exp_f32_e32 v18, v18
	ds_read_u16 v19, v175
	ds_read_u16 v20, v175 offset:16384
	s_waitcnt lgkmcnt(1)
	v_lshlrev_b32_e32 v19, 16, v19
	s_waitcnt lgkmcnt(0)
	v_lshlrev_b32_e32 v20, 16, v20
	v_mul_f32_e32 v18, v18, v19
	v_cvt_pk_bf16_f32 v18, v18, s0
	ds_write_b16 v175, v18
	v_mul_f32_e32 v18, v21, v20
	v_cvt_pk_bf16_f32 v18, v18, s0
	ds_write_b16 v175, v18 offset:16384
	v_mul_f32_e32 v18, v16, v21
	v_mul_f32_e32 v18, v18, v20
	v_cvt_pk_bf16_f32 v18, v18, s0
	ds_write_b16 v176, v18 offset:32768
	v_add_f32_e32 v18, v32, v17
	v_mul_f32_e32 v18, 0x3fb8aa3b, v18
	v_exp_f32_e64 v21, -v18
	v_exp_f32_e32 v18, v18
	ds_read_u16 v19, v177
	ds_read_u16 v20, v177 offset:16384
	s_waitcnt lgkmcnt(1)
	v_lshlrev_b32_e32 v19, 16, v19
	s_waitcnt lgkmcnt(0)
	v_lshlrev_b32_e32 v20, 16, v20
	v_mul_f32_e32 v18, v18, v19
	v_cvt_pk_bf16_f32 v18, v18, s0
	ds_write_b16 v177, v18
	v_mul_f32_e32 v18, v21, v20
	v_cvt_pk_bf16_f32 v18, v18, s0
	ds_write_b16 v177, v18 offset:16384
	v_mul_f32_e32 v18, v16, v21
	v_mul_f32_e32 v18, v18, v20
	v_cvt_pk_bf16_f32 v18, v18, s0
	ds_write_b16 v178, v18 offset:32768
	v_add_f32_e32 v18, v33, v17
	v_mul_f32_e32 v18, 0x3fb8aa3b, v18
	v_exp_f32_e64 v21, -v18
	v_exp_f32_e32 v18, v18
	ds_read_u16 v19, v179
	ds_read_u16 v20, v179 offset:16384
	s_waitcnt lgkmcnt(1)
	v_lshlrev_b32_e32 v19, 16, v19
	s_waitcnt lgkmcnt(0)
	v_lshlrev_b32_e32 v20, 16, v20
	v_mul_f32_e32 v18, v18, v19
	v_cvt_pk_bf16_f32 v18, v18, s0
	ds_write_b16 v179, v18
	v_mul_f32_e32 v18, v21, v20
	v_cvt_pk_bf16_f32 v18, v18, s0
	ds_write_b16 v179, v18 offset:16384
	v_mul_f32_e32 v18, v16, v21
	v_mul_f32_e32 v18, v18, v20
	v_cvt_pk_bf16_f32 v18, v18, s0
	ds_write_b16 v180, v18 offset:32768
	v_add_f32_e32 v18, v34, v17
	v_mul_f32_e32 v18, 0x3fb8aa3b, v18
	v_exp_f32_e64 v21, -v18
	v_exp_f32_e32 v18, v18
	ds_read_u16 v19, v181
	ds_read_u16 v20, v181 offset:16384
	v_add_f32_e32 v17, v35, v17
	v_mul_f32_e32 v17, 0x3fb8aa3b, v17
	s_waitcnt lgkmcnt(1)
	v_lshlrev_b32_e32 v19, 16, v19
	s_waitcnt lgkmcnt(0)
	v_lshlrev_b32_e32 v20, 16, v20
	v_exp_f32_e32 v17, v17
	v_mul_f32_e32 v18, v18, v19
	v_cvt_pk_bf16_f32 v18, v18, s0
	ds_write_b16 v181, v18
	v_mul_f32_e32 v18, v21, v20
	v_cvt_pk_bf16_f32 v18, v18, s0
	ds_write_b16 v181, v18 offset:16384
	v_mul_f32_e32 v18, v16, v21
	v_mul_f32_e32 v18, v18, v20
	v_div_scale_f32 v20, s[2:3], v17, v17, 1.0
	v_rcp_f32_e32 v21, v20
	v_cvt_pk_bf16_f32 v18, v18, s0
	ds_write_b16 v182, v18 offset:32768
	ds_read_u16 v18, v183
	ds_read_u16 v19, v183 offset:16384
	v_fma_f32 v22, -v20, v21, 1.0
	v_fmac_f32_e32 v21, v22, v21
	v_div_scale_f32 v22, vcc, 1.0, v17, 1.0
	v_mul_f32_e32 v23, v22, v21
	v_fma_f32 v24, -v20, v23, v22
	v_fmac_f32_e32 v23, v24, v21
	v_fma_f32 v20, -v20, v23, v22
	s_waitcnt lgkmcnt(1)
	v_lshlrev_b32_e32 v18, 16, v18
	v_div_fmas_f32 v20, v20, v21, v23
	v_div_fixup_f32 v20, v20, v17, 1.0
	v_mul_f32_e32 v17, v17, v18
	s_waitcnt lgkmcnt(0)
	v_lshlrev_b32_e32 v19, 16, v19
	v_cvt_pk_bf16_f32 v17, v17, s0
	v_mul_f32_e32 v16, v16, v20
	ds_write_b16 v183, v17
	v_mul_f32_e32 v17, v20, v19
	v_mul_f32_e32 v16, v16, v19
	v_cvt_pk_bf16_f32 v17, v17, s0
	v_cvt_pk_bf16_f32 v16, v16, s0
	ds_write_b16 v183, v17 offset:16384
	ds_write_b16 v184, v16 offset:32768
	s_waitcnt lgkmcnt(0)
	s_barrier
	s_and_saveexec_b64 s[2:3], s[8:9]
	s_cbranch_execz .LBB0_396
; DEVI int crow(int r, int hi) { return (r & 3) + 8 * (r >> 2) + 4 * hi; }
; DEVI void gla_seq(const Params& p, int l, int item, char* lds) {
;     ...
;       const int irow = iblk * 32 + r32;
; #pragma unroll
;       for (int d0 = 0; d0 < 8; ++d0) {
;         const int chn = d0 * 2 + hi;
;         const bf16x8 b0 = *(const bf16x8*)(ks + r32 * 256 + ((chn ^ (r32 & 7)) << 4));
;         const bf16x8 b1 = *(const bf16x8*)(ks + (32 + r32) * 256 + ((chn ^ (r32 & 7)) << 4));
;         const bf16x8 qf = *(const bf16x8*)(qs + irow * 256 + ((chn ^ (irow & 7)) << 4));
;         p0 = __builtin_amdgcn_mfma_f32_32x32x16_bf16(b0, qf, p0, 0, 0, 0);
;         p1 = __builtin_amdgcn_mfma_f32_32x32x16_bf16(b1, qf, p1, 0, 0, 0);
;       }
; #pragma unroll
;       for (int r = 0; r < 16; ++r) {
;         const int j0 = crow(r, hi), j1 = 32 + j0;
;         const bool k0 = dir ? (j0 < irow) : (j0 <= irow), k1 = dir ? (j1 < irow) : (j1 <= irow);
;         p0[r] = k0 ? p0[r] : 0.f; p1[r] = k1 ? p1[r] : 0.f;
;       }
;       bf16x8 pa0, pa1, pa2, pa3;
;       PK4(p0, 0, pa0); PK4(p0, 8, pa1); PK4(p1, 0, pa2); PK4(p1, 8, pa3);
;       const char* vrow = vT + (eblk * 32 + r32) * 144 + hi * 16;
;       o = __builtin_amdgcn_mfma_f32_32x32x16_bf16(pa0, *(const bf16x8*)(vrow), o, 0, 0, 0);
;       o = __builtin_amdgcn_mfma_f32_32x32x16_bf16(pa1, *(const bf16x8*)(vrow + 32), o, 0, 0, 0);
;       o = __builtin_amdgcn_mfma_f32_32x32x16_bf16(pa2, *(const bf16x8*)(vrow + 64), o, 0, 0, 0);
	v_add_u32_e32 v32, v137, v139
	ds_read_b128 v[16:19], v32 offset:16384
	v_add_u32_e32 v20, v138, v139
	ds_read_b128 v[68:71], v20
	v_add_u32_e32 v80, v137, v140
	ds_read_b128 v[76:79], v80 offset:16384
	ds_read_b128 v[32:35], v32 offset:24576
	v_add_u32_e32 v72, v138, v140
	ds_read_b128 v[72:75], v72
	v_add_u32_e32 v84, v137, v141
	s_waitcnt lgkmcnt(3)
	v_mfma_f32_32x32x16_bf16 v[16:31], v[16:19], v[68:71], 0
	v_add_u32_e32 v88, v137, v142
	v_add_u32_e32 v92, v137, v143
	v_add_u32_e32 v96, v137, v144
	v_add_u32_e32 v188, v137, v145
	v_add_u32_e32 v194, v137, v146
	v_readlane_b32 s68, v254, 30
	v_readlane_b32 s69, v254, 31
	s_waitcnt lgkmcnt(0)
	v_mfma_f32_32x32x16_bf16 v[16:31], v[76:79], v[72:75], v[16:31]
	ds_read_b128 v[76:79], v80 offset:24576
	ds_read_b128 v[80:83], v84 offset:16384
	s_add_i32 s27, s93, 0xffffff00
	s_cmp_lt_u32 s46, 4
	s_cselect_b32 s27, s93, s27
	s_cselect_b32 s29, 0x2000, 0
	v_mfma_f32_32x32x16_bf16 v[32:47], v[32:35], v[68:71], 0
	s_waitcnt lgkmcnt(1)
	v_mfma_f32_32x32x16_bf16 v[32:47], v[76:79], v[72:75], v[32:47]
	v_add_u32_e32 v76, v138, v141
	ds_read_b128 v[76:79], v76
	s_waitcnt lgkmcnt(0)
	v_mfma_f32_32x32x16_bf16 v[16:31], v[80:83], v[76:79], v[16:31]
	ds_read_b128 v[80:83], v84 offset:24576
	ds_read_b128 v[84:87], v88 offset:16384
	s_waitcnt lgkmcnt(1)
	v_mfma_f32_32x32x16_bf16 v[32:47], v[80:83], v[76:79], v[32:47]
	v_add_u32_e32 v80, v138, v142
	ds_read_b128 v[80:83], v80
	s_waitcnt lgkmcnt(0)
	v_mfma_f32_32x32x16_bf16 v[16:31], v[84:87], v[80:83], v[16:31]
	ds_read_b128 v[84:87], v88 offset:24576
	ds_read_b128 v[88:91], v92 offset:16384
	s_waitcnt lgkmcnt(1)
	v_mfma_f32_32x32x16_bf16 v[32:47], v[84:87], v[80:83], v[32:47]
	v_add_u32_e32 v84, v138, v143
	ds_read_b128 v[84:87], v84
	s_waitcnt lgkmcnt(0)
	v_mfma_f32_32x32x16_bf16 v[16:31], v[88:91], v[84:87], v[16:31]
	ds_read_b128 v[88:91], v92 offset:24576
	ds_read_b128 v[92:95], v96 offset:16384
	s_waitcnt lgkmcnt(1)
	v_mfma_f32_32x32x16_bf16 v[32:47], v[88:91], v[84:87], v[32:47]
	v_add_u32_e32 v88, v138, v144
	ds_read_b128 v[88:91], v88
	s_waitcnt lgkmcnt(0)
	v_mfma_f32_32x32x16_bf16 v[16:31], v[92:95], v[88:91], v[16:31]
	ds_read_b128 v[92:95], v96 offset:24576
	ds_read_b128 v[96:99], v188 offset:16384
	s_waitcnt lgkmcnt(1)
	v_mfma_f32_32x32x16_bf16 v[32:47], v[92:95], v[88:91], v[32:47]
	v_add_u32_e32 v92, v138, v145
	ds_read_b128 v[92:95], v92
	s_waitcnt lgkmcnt(0)
	v_mfma_f32_32x32x16_bf16 v[16:31], v[96:99], v[92:95], v[16:31]
	ds_read_b128 v[96:99], v188 offset:24576
	ds_read_b128 v[188:191], v194 offset:16384
	s_waitcnt lgkmcnt(1)
	v_mfma_f32_32x32x16_bf16 v[32:47], v[96:99], v[92:95], v[32:47]
	v_add_u32_e32 v96, v138, v146
	ds_read_b128 v[96:99], v96
	s_waitcnt lgkmcnt(0)
	v_mfma_f32_32x32x16_bf16 v[16:31], v[188:191], v[96:99], v[16:31]
	ds_read_b128 v[188:191], v194 offset:24576
	s_waitcnt lgkmcnt(0)
	v_mfma_f32_32x32x16_bf16 v[32:47], v[188:191], v[96:99], v[32:47]
	s_nop 8
	v_cndmask_b32_e64 v16, 0, v16, s[72:73]
	v_cndmask_b32_e64 v27, 0, v27, s[50:51]
	v_cndmask_b32_e64 v28, 0, v28, s[38:39]
	v_cndmask_b32_e64 v29, 0, v29, s[42:43]
	v_cndmask_b32_e64 v30, 0, v30, s[76:77]
	v_cndmask_b32_e64 v31, 0, v31, s[80:81]
	v_cndmask_b32_e64 v188, 0, v32, s[68:69]
	v_readlane_b32 s68, v254, 32
	v_readlane_b32 s69, v254, 33
	v_cndmask_b32_e64 v199, 0, v42, s[48:49]
	v_cndmask_b32_e64 v200, 0, v43, s[30:31]
	v_cndmask_b32_e64 v17, 0, v17, s[68:69]
	v_readlane_b32 s68, v254, 34
	v_readlane_b32 s69, v254, 35
	v_cvt_pk_bf16_f32 v16, v16, v17
	v_cndmask_b32_e64 v44, 0, v44, s[40:41]
	v_cndmask_b32_e64 v189, 0, v33, s[68:69]
	v_readlane_b32 s68, v254, 36
	v_readlane_b32 s69, v254, 37
	v_cndmask_b32_e64 v45, 0, v45, s[44:45]
	v_cndmask_b32_e64 v46, 0, v46, s[78:79]
	v_cndmask_b32_e64 v18, 0, v18, s[68:69]
	v_readlane_b32 s68, v254, 38
	v_readlane_b32 s69, v254, 39
	v_cndmask_b32_e64 v47, 0, v47, s[82:83]
	s_nop 0
	v_cndmask_b32_e64 v190, 0, v34, s[68:69]
	v_readlane_b32 s68, v254, 40
	v_readlane_b32 s69, v254, 41
	v_cvt_pk_bf16_f32 v34, v28, v29
	s_nop 0
	v_cndmask_b32_e64 v19, 0, v19, s[68:69]
	v_readlane_b32 s68, v254, 42
	v_readlane_b32 s69, v254, 43
	v_cvt_pk_bf16_f32 v17, v18, v19
	s_nop 0
	v_cndmask_b32_e64 v191, 0, v35, s[68:69]
	v_readlane_b32 s68, v254, 44
	v_readlane_b32 s69, v254, 45
	v_cvt_pk_bf16_f32 v35, v30, v31
	s_nop 0
	v_cndmask_b32_e64 v20, 0, v20, s[68:69]
	v_readlane_b32 s68, v254, 46
	v_readlane_b32 s69, v254, 47
	s_nop 1
	v_cndmask_b32_e64 v194, 0, v36, s[68:69]
	v_readlane_b32 s68, v254, 48
	v_readlane_b32 s69, v254, 49
	v_cvt_pk_bf16_f32 v36, v188, v189
	s_nop 0
	v_cndmask_b32_e64 v21, 0, v21, s[68:69]
	v_readlane_b32 s68, v254, 50
	v_readlane_b32 s69, v254, 51
	v_cvt_pk_bf16_f32 v18, v20, v21
	s_nop 1
	v_permlane32_swap_b32_e32 v16, v18
	v_cndmask_b32_e64 v195, 0, v37, s[68:69]
	v_readlane_b32 s68, v254, 52
	v_readlane_b32 s69, v254, 53
	v_cvt_pk_bf16_f32 v37, v190, v191
	s_nop 0
	v_cndmask_b32_e64 v22, 0, v22, s[68:69]
	v_readlane_b32 s68, v254, 54
	v_readlane_b32 s69, v254, 55
	s_nop 1
	v_cndmask_b32_e64 v196, 0, v38, s[68:69]
	v_readlane_b32 s68, v254, 56
	v_readlane_b32 s69, v254, 57
	v_cvt_pk_bf16_f32 v38, v194, v195
	s_nop 1
	v_permlane32_swap_b32_e32 v36, v38
	v_cndmask_b32_e64 v23, 0, v23, s[68:69]
	v_readlane_b32 s68, v254, 58
	v_readlane_b32 s69, v254, 59
	v_cvt_pk_bf16_f32 v19, v22, v23
	s_nop 1
	v_permlane32_swap_b32_e32 v17, v19
	v_cndmask_b32_e64 v39, 0, v39, s[68:69]
	v_readlane_b32 s68, v254, 60
	v_readlane_b32 s69, v254, 61
	ds_read_b128 v[20:23], v187 offset:51200
	v_cvt_pk_bf16_f32 v39, v196, v39
	v_cndmask_b32_e64 v24, 0, v24, s[68:69]
	v_readlane_b32 s68, v254, 62
	v_readlane_b32 s69, v254, 63
	v_permlane32_swap_b32_e32 v37, v39
	s_nop 0
	v_cndmask_b32_e64 v197, 0, v40, s[68:69]
	v_readlane_b32 s68, v255, 0
	v_readlane_b32 s69, v255, 1
	s_nop 1
	v_cndmask_b32_e64 v25, 0, v25, s[68:69]
	v_readlane_b32 s68, v255, 2
	v_readlane_b32 s69, v255, 3
	v_cvt_pk_bf16_f32 v32, v24, v25
	s_nop 1
	v_permlane32_swap_b32_e32 v32, v34
	v_cndmask_b32_e64 v198, 0, v41, s[68:69]
	v_readlane_b32 s68, v255, 4
	v_readlane_b32 s69, v255, 5
	ds_read_b128 v[40:43], v187 offset:51232
	s_nop 0
	v_cndmask_b32_e64 v26, 0, v26, s[68:69]
	v_cvt_pk_bf16_f32 v33, v26, v27
	s_waitcnt lgkmcnt(1)
; DEVI void gla_seq(const Params& p, int l, int item, char* lds) {
;     ...
;       const char* vrow = vT + (eblk * 32 + r32) * 144 + hi * 16;
;       o = __builtin_amdgcn_mfma_f32_32x32x16_bf16(pa0, *(const bf16x8*)(vrow), o, 0, 0, 0);
;       o = __builtin_amdgcn_mfma_f32_32x32x16_bf16(pa1, *(const bf16x8*)(vrow + 32), o, 0, 0, 0);
;       o = __builtin_amdgcn_mfma_f32_32x32x16_bf16(pa2, *(const bf16x8*)(vrow + 64), o, 0, 0, 0);
;       o = __builtin_amdgcn_mfma_f32_32x32x16_bf16(pa3, *(const bf16x8*)(vrow + 96), o, 0, 0, 0);
;       const int erow = eblk * 32 + r32;
; #pragma unroll
;       for (int d0 = 0; d0 < 8; ++d0) {
;         const int chn = d0 * 2 + hi;
;         const bf16x8 qf = *(const bf16x8*)(qs + irow * 256 + ((chn ^ (irow & 7)) << 4));
;         const bf16x8 sf = *(const bf16x8*)(sTc + erow * 256 + ((chn ^ (erow & 7)) << 4));
;         o = __builtin_amdgcn_mfma_f32_32x32x16_bf16(qf, sf, o, 0, 0, 0);
;       }
	v_mfma_f32_32x32x16_bf16 v[16:31], v[16:19], v[20:23], 0
	v_permlane32_swap_b32_e32 v33, v35
	v_readlane_b32 s68, v253, 21
	s_waitcnt lgkmcnt(0)
	v_mfma_f32_32x32x16_bf16 v[16:31], v[32:35], v[40:43], v[16:31]
	ds_read_b128 v[40:43], v187 offset:51264
	v_cvt_pk_bf16_f32 v32, v197, v198
	v_cvt_pk_bf16_f32 v33, v199, v200
	v_cvt_pk_bf16_f32 v34, v44, v45
	v_cvt_pk_bf16_f32 v35, v46, v47
	s_nop 0
	v_permlane32_swap_b32_e32 v32, v34
	s_waitcnt lgkmcnt(0)
	v_mfma_f32_32x32x16_bf16 v[16:31], v[36:39], v[40:43], v[16:31]
	v_permlane32_swap_b32_e32 v33, v35
	ds_read_b128 v[36:39], v187 offset:51296
	s_waitcnt lgkmcnt(0)
	v_mfma_f32_32x32x16_bf16 v[16:31], v[32:35], v[36:39], v[16:31]
	v_lshl_add_u32 v36, s75, 14, v134
	v_add_u32_e32 v32, v36, v139
	ds_read_b128 v[32:35], v32 offset:60416
	s_waitcnt lgkmcnt(0)
	v_mfma_f32_32x32x16_bf16 v[16:31], v[68:71], v[32:35], v[16:31]
	v_add_u32_e32 v32, v36, v140
	ds_read_b128 v[32:35], v32 offset:60416
	s_waitcnt lgkmcnt(0)
	v_mfma_f32_32x32x16_bf16 v[16:31], v[72:75], v[32:35], v[16:31]
	v_add_u32_e32 v32, v36, v141
	ds_read_b128 v[32:35], v32 offset:60416
	s_waitcnt lgkmcnt(0)
	v_mfma_f32_32x32x16_bf16 v[16:31], v[76:79], v[32:35], v[16:31]
	v_add_u32_e32 v32, v36, v142
	ds_read_b128 v[32:35], v32 offset:60416
	s_waitcnt lgkmcnt(0)
	v_mfma_f32_32x32x16_bf16 v[16:31], v[80:83], v[32:35], v[16:31]
	v_add_u32_e32 v32, v36, v143
	ds_read_b128 v[32:35], v32 offset:60416
	s_waitcnt lgkmcnt(0)
	v_mfma_f32_32x32x16_bf16 v[16:31], v[84:87], v[32:35], v[16:31]
	v_add_u32_e32 v32, v36, v144
	ds_read_b128 v[32:35], v32 offset:60416
	s_waitcnt lgkmcnt(0)
	v_mfma_f32_32x32x16_bf16 v[16:31], v[88:91], v[32:35], v[16:31]
	v_add_u32_e32 v32, v36, v145
	ds_read_b128 v[32:35], v32 offset:60416
	v_add_u32_e32 v36, v36, v146
	ds_read_b128 v[36:39], v36 offset:60416
	s_waitcnt lgkmcnt(1)
	v_mfma_f32_32x32x16_bf16 v[16:31], v[92:95], v[32:35], v[16:31]
	v_or_b32_e32 v34, s27, v151
	s_cselect_b32 s27, 0xff, s61
	v_sub_u32_e32 v32, s27, v34
	s_add_i32 s29, s29, s68
	v_cndmask_b32_e64 v32, v32, v34, s[4:5]
	v_add_u32_e32 v32, s29, v32
	v_ashrrev_i32_e32 v33, 31, v32
	s_waitcnt lgkmcnt(0)
; DEVI u16 f2bf(float f) { return (u16)(cvtpk(f, 0.f) & 0xffffu); }
; DEVI int crow(int r, int hi) { return (r & 3) + 8 * (r >> 2) + 4 * hi; }
; DEVI long gla_row(int bi, int dir, int cc, int i) {
;   const int L = (cc < 4) ? CTXL : SEQ, c = (cc < 4) ? cc : cc - 4, rb = bi * ROWS + ((cc < 4) ? SEQ : 0);
;   const int tl = c * 64 + i;
;   return (long)(rb + (dir ? (L - 1 - tl) : tl));
; }
; DEVI void gla_seq(const Params& p, int l, int item, char* lds) {
;     ...
; #pragma unroll
;       for (int r = 0; r < 16; ++r)
;         og[gla_row(bi, dir, cc, iblk * 32 + crow(r, hi)) * 1024 + h * 256 + sl * 64 + eblk * 32 + r32] = f2bf(o[r]);
	v_mfma_f32_32x32x16_bf16 v[16:31], v[96:99], v[36:39], v[16:31]
	v_lshlrev_b64 v[32:33], 11, v[32:33]
	v_lshl_add_u64 v[32:33], v[102:103], 0, v[32:33]
	s_nop 9
	v_cvt_pk_bf16_f32 v16, v16, s0
	global_store_short v[32:33], v16, off
	v_or_b32_e32 v16, 1, v34
	v_cvt_pk_bf16_f32 v32, v17, s0
	v_sub_u32_e32 v17, s27, v16
	v_cndmask_b32_e64 v16, v17, v16, s[4:5]
	v_add_u32_e32 v16, s29, v16
	v_ashrrev_i32_e32 v17, 31, v16
	v_lshlrev_b64 v[16:17], 11, v[16:17]
	v_lshl_add_u64 v[16:17], v[102:103], 0, v[16:17]
	global_store_short v[16:17], v32, off
	v_or_b32_e32 v16, 2, v34
	v_sub_u32_e32 v17, s27, v16
	v_cndmask_b32_e64 v16, v17, v16, s[4:5]
	v_add_u32_e32 v16, s29, v16
	v_ashrrev_i32_e32 v17, 31, v16
	v_lshlrev_b64 v[16:17], 11, v[16:17]
	v_cvt_pk_bf16_f32 v18, v18, s0
	v_lshl_add_u64 v[16:17], v[102:103], 0, v[16:17]
	global_store_short v[16:17], v18, off
	v_or_b32_e32 v16, 3, v34
	v_sub_u32_e32 v17, s27, v16
	v_cndmask_b32_e64 v16, v17, v16, s[4:5]
	v_add_u32_e32 v16, s29, v16
	v_ashrrev_i32_e32 v17, 31, v16
	v_lshlrev_b64 v[16:17], 11, v[16:17]
	v_cvt_pk_bf16_f32 v18, v19, s0
	v_lshl_add_u64 v[16:17], v[102:103], 0, v[16:17]
	global_store_short v[16:17], v18, off
	v_or_b32_e32 v16, 8, v34
	v_sub_u32_e32 v17, s27, v16
	v_cndmask_b32_e64 v16, v17, v16, s[4:5]
	v_add_u32_e32 v16, s29, v16
	v_ashrrev_i32_e32 v17, 31, v16
	v_lshlrev_b64 v[16:17], 11, v[16:17]
	v_cvt_pk_bf16_f32 v18, v20, s0
	v_lshl_add_u64 v[16:17], v[102:103], 0, v[16:17]
	global_store_short v[16:17], v18, off
	v_or_b32_e32 v16, 9, v34
	v_sub_u32_e32 v17, s27, v16
	v_cndmask_b32_e64 v16, v17, v16, s[4:5]
	v_add_u32_e32 v16, s29, v16
	v_ashrrev_i32_e32 v17, 31, v16
	v_lshlrev_b64 v[16:17], 11, v[16:17]
	v_cvt_pk_bf16_f32 v18, v21, s0
	v_lshl_add_u64 v[16:17], v[102:103], 0, v[16:17]
	global_store_short v[16:17], v18, off
	v_or_b32_e32 v16, 10, v34
	v_sub_u32_e32 v17, s27, v16
	v_cndmask_b32_e64 v16, v17, v16, s[4:5]
	v_add_u32_e32 v16, s29, v16
	v_ashrrev_i32_e32 v17, 31, v16
	v_lshlrev_b64 v[16:17], 11, v[16:17]
	v_cvt_pk_bf16_f32 v18, v22, s0
	v_lshl_add_u64 v[16:17], v[102:103], 0, v[16:17]
	global_store_short v[16:17], v18, off
	v_or_b32_e32 v16, 11, v34
	v_sub_u32_e32 v17, s27, v16
	v_cndmask_b32_e64 v16, v17, v16, s[4:5]
	v_add_u32_e32 v16, s29, v16
	v_ashrrev_i32_e32 v17, 31, v16
	v_lshlrev_b64 v[16:17], 11, v[16:17]
	v_cvt_pk_bf16_f32 v18, v23, s0
	v_lshl_add_u64 v[16:17], v[102:103], 0, v[16:17]
	global_store_short v[16:17], v18, off
	v_or_b32_e32 v16, 16, v34
	v_sub_u32_e32 v17, s27, v16
	v_cndmask_b32_e64 v16, v17, v16, s[4:5]
	v_add_u32_e32 v16, s29, v16
	v_ashrrev_i32_e32 v17, 31, v16
	v_lshlrev_b64 v[16:17], 11, v[16:17]
	v_cvt_pk_bf16_f32 v18, v24, s0
	v_lshl_add_u64 v[16:17], v[102:103], 0, v[16:17]
	global_store_short v[16:17], v18, off
	v_or_b32_e32 v16, 17, v34
	v_sub_u32_e32 v17, s27, v16
	v_cndmask_b32_e64 v16, v17, v16, s[4:5]
	v_add_u32_e32 v16, s29, v16
	v_ashrrev_i32_e32 v17, 31, v16
	v_lshlrev_b64 v[16:17], 11, v[16:17]
	v_cvt_pk_bf16_f32 v18, v25, s0
	v_lshl_add_u64 v[16:17], v[102:103], 0, v[16:17]
	global_store_short v[16:17], v18, off
	v_or_b32_e32 v16, 18, v34
	v_sub_u32_e32 v17, s27, v16
	v_cndmask_b32_e64 v16, v17, v16, s[4:5]
	v_add_u32_e32 v16, s29, v16
	v_ashrrev_i32_e32 v17, 31, v16
	v_lshlrev_b64 v[16:17], 11, v[16:17]
	v_cvt_pk_bf16_f32 v18, v26, s0
	v_lshl_add_u64 v[16:17], v[102:103], 0, v[16:17]
	global_store_short v[16:17], v18, off
	v_or_b32_e32 v16, 19, v34
	v_sub_u32_e32 v17, s27, v16
	v_cndmask_b32_e64 v16, v17, v16, s[4:5]
	v_add_u32_e32 v16, s29, v16
	v_ashrrev_i32_e32 v17, 31, v16
	v_lshlrev_b64 v[16:17], 11, v[16:17]
	v_cvt_pk_bf16_f32 v18, v27, s0
	v_lshl_add_u64 v[16:17], v[102:103], 0, v[16:17]
	global_store_short v[16:17], v18, off
	v_or_b32_e32 v16, 24, v34
	v_sub_u32_e32 v17, s27, v16
	v_cndmask_b32_e64 v16, v17, v16, s[4:5]
	v_add_u32_e32 v16, s29, v16
	v_ashrrev_i32_e32 v17, 31, v16
	v_lshlrev_b64 v[16:17], 11, v[16:17]
	v_cvt_pk_bf16_f32 v18, v28, s0
	v_lshl_add_u64 v[16:17], v[102:103], 0, v[16:17]
	global_store_short v[16:17], v18, off
	v_or_b32_e32 v16, 25, v34
	v_sub_u32_e32 v17, s27, v16
	v_cndmask_b32_e64 v16, v17, v16, s[4:5]
	v_add_u32_e32 v16, s29, v16
	v_ashrrev_i32_e32 v17, 31, v16
	v_lshlrev_b64 v[16:17], 11, v[16:17]
	v_cvt_pk_bf16_f32 v18, v29, s0
	v_lshl_add_u64 v[16:17], v[102:103], 0, v[16:17]
	global_store_short v[16:17], v18, off
	v_or_b32_e32 v16, 26, v34
	v_sub_u32_e32 v17, s27, v16
	v_cndmask_b32_e64 v16, v17, v16, s[4:5]
	v_add_u32_e32 v16, s29, v16
	v_ashrrev_i32_e32 v17, 31, v16
	v_lshlrev_b64 v[16:17], 11, v[16:17]
	v_cvt_pk_bf16_f32 v18, v30, s0
	v_lshl_add_u64 v[16:17], v[102:103], 0, v[16:17]
	global_store_short v[16:17], v18, off
	v_or_b32_e32 v16, 27, v34
	v_sub_u32_e32 v17, s27, v16
	v_cndmask_b32_e64 v16, v17, v16, s[4:5]
	v_add_u32_e32 v16, s29, v16
	v_ashrrev_i32_e32 v17, 31, v16
	v_lshlrev_b64 v[16:17], 11, v[16:17]
	v_cvt_pk_bf16_f32 v18, v31, s0
	v_lshl_add_u64 v[16:17], v[102:103], 0, v[16:17]
	global_store_short v[16:17], v18, off
	s_branch .LBB0_396
